# row pass: counted wait (vmcnt(4)) at the top of the iteration instead of a full drain
# baseline (speedup 1.0000x reference)
.Lrpa_3:
	s_lshl_b32 s99, s99, 12
	s_add_u32 s100, s100, s99
	s_addc_u32 s101, s101, 0
	global_load_dwordx4 v[160:163], v42, s[100:101] nt
	global_load_dwordx4 v[164:167], v42, s[100:101] offset:1024 nt
	global_load_dwordx4 v[168:171], v42, s[100:101] offset:2048 nt
	global_load_dwordx4 v[172:175], v42, s[100:101] offset:3072 nt
	s_waitcnt vmcnt(0)
	s_branch .LBB0_179

.LBB0_185:
	s_or_saveexec_b64 s[6:7], s[6:7]
	v_ashrrev_i32_e32 v47, 31, v46
	s_xor_b64 exec, exec, s[6:7]
	v_mov_b64_e32 v[2:3], v[46:47]
	s_or_b64 exec, exec, s[6:7]
	v_lshlrev_b64 v[2:3], 12, v[2:3]
	v_lshl_add_u64 v[0:1], v[0:1], 0, v[2:3]
	v_lshl_add_u64 v[0:1], v[0:1], 0, v[42:43]
	s_waitcnt vmcnt(4)
	v_mov_b32_e32 v36, v160
	v_mov_b32_e32 v37, v161
	v_mov_b32_e32 v38, v162
	v_mov_b32_e32 v39, v163
	v_mov_b32_e32 v32, v164
	v_mov_b32_e32 v33, v165
	v_mov_b32_e32 v34, v166
	v_mov_b32_e32 v35, v167
	v_mov_b32_e32 v28, v168
	v_mov_b32_e32 v29, v169
	v_mov_b32_e32 v30, v170
	v_mov_b32_e32 v31, v171
	v_mov_b32_e32 v24, v172
	v_mov_b32_e32 v25, v173
	v_mov_b32_e32 v26, v174
	v_mov_b32_e32 v27, v175
	v_add_u32_e32 v44, s42, v46
	v_cmp_gt_i32_e64 s[6:7], s2, v44
	s_and_saveexec_b64 s[8:9], s[6:7]
	s_cbranch_execz .LBB0_197
	v_cmp_lt_i32_e32 vcc, s43, v44
	v_mov_b64_e32 v[0:1], s[20:21]
	s_and_saveexec_b64 s[24:25], vcc
	s_xor_b64 s[24:25], exec, s[24:25]
	s_cbranch_execz .LBB0_194
	v_cmp_lt_u32_e32 vcc, s56, v44
	v_mov_b64_e32 v[0:1], s[22:23]
	s_and_saveexec_b64 s[28:29], vcc
	s_xor_b64 s[28:29], exec, s[28:29]
	v_add_u32_e32 v2, 0xffffbe00, v44
	v_mov_b32_e32 v3, v43
	v_mov_b64_e32 v[0:1], s[46:47]
	s_andn2_saveexec_b64 s[28:29], s[28:29]
	v_add_u32_e32 v2, 0xffffc000, v44
	v_mov_b32_e32 v3, v43
	s_or_b64 exec, exec, s[28:29]
